# v15 + P8 wave-index renumbering: the 128 sample top-k rows (long single-wave items) moved from 8-per-workgroup on 16 workgroups to one per workgroup (wave 7 of workgroups 128-255)
# speedup vs baseline: 1.0092x; 1.0092x over previous
; #define LAS __attribute__((address_space(3)))
; DI float bf2f(unsigned b) { return __uint_as_float(b << 16); }
; DI void dsa_post_row(const float* KRAW, const float* KIRAW, const float* knorm, const float* kinorm, float* kout, float* kiout, bf16* KB, bf16* KIB, const bf16* VB, unsigned char* K8, unsigned char* V8, int t, int lane) {
;     { const float* p = KRAW + (size_t)t * 512 + 8 * lane; f32x4 a = *(const f32x4*)p, b = *(const f32x4*)(p + 4);
;       const float rs = rsqrtf(grp16_sum((a.x * a.x + a.y * a.y) + (a.z * a.z + a.w * a.w) + (b.x * b.x + b.y * b.y) + (b.z * b.z + b.w * b.w)) * (1.f / 128.f) + EPS);
;       const float* gp = knorm + ((8 * lane) & 127); const f32x4 g0 = *(const f32x4*)gp, g1 = *(const f32x4*)(gp + 4);
;       a = a * rs * g0; b = b * rs * g1; float* o = kout + (size_t)t * 512 + 8 * lane; __builtin_nontemporal_store(a, (f32x4*)o); __builtin_nontemporal_store(b, (f32x4*)(o + 4)); *(bf16x8*)(KB + (size_t)t * 512 + 8 * lane) = pack8(a, b);
;       *(v2u*)(K8 + (size_t)t * 512 + 8 * lane) = (v2u){pk4_fp8(a[0], a[1], a[2], a[3]), pk4_fp8(b[0], b[1], b[2], b[3])};
;       const v4u vw = *(const v4u*)(VB + (size_t)t * 512 + 8 * lane);
;       *(v2u*)(V8 + (size_t)t * 512 + 8 * lane) = (v2u){pk4_fp8(bf2f(vw.x & 0xffffu), bf2f(vw.x >> 16), bf2f(vw.y & 0xffffu), bf2f(vw.y >> 16)), pk4_fp8(bf2f(vw.z & 0xffffu), bf2f(vw.z >> 16), bf2f(vw.w & 0xffffu), bf2f(vw.w >> 16))}; }
;     { const f32x2 a = *(const f32x2*)(KIRAW + (size_t)t * 128 + 2 * lane); const float rs = rsqrtf(wave_sum(a.x * a.x + a.y * a.y) * (1.f / 128.f) + EPS);
;       const f32x2 gk = *(const f32x2*)(kinorm + 2 * lane); const float x = a.x * rs * gk.x, y = a.y * rs * gk.y;
;       *(f32x2*)(kiout + (size_t)t * 128 + 2 * lane) = (f32x2){x, y}; *(unsigned*)(KIB + (size_t)t * 128 + 2 * lane) = pk2(x, y); }
; }
; __global__ void __launch_bounds__(NTHR, 2) mk_fwd(Args args) {
;     ...
;         if (gw < NGW - BS) for (int t = gw; t < T; t += NGW - BS) dsa_post_row(KRAW, KIRAW, b_k_norm, b_ki_norm, out + O_KP, out + O_KIP, KB, KIB, VB, (unsigned char*)(AP->ws + WS_K8), (unsigned char*)(AP->ws + WS_V8), t, lane);
;         for (int b = NGW - 1 - gw; b < BS; b += NGW) topk_dispatch(SCS + (size_t)b * SCS_LD, PAST + 1, IDXS + b * TOPK, (LAS unsigned*)(lds + wave * 8192), lane);
.LBB0_995:
	s_cmp_lt_i32 s26, 9
	s_cselect_b64 s[4:5], -1, 0
	s_cmp_gt_i32 s27, 8
	s_cselect_b64 s[6:7], -1, 0
	s_and_b64 s[4:5], s[4:5], s[6:7]
	s_andn2_b64 vcc, exec, s[4:5]
	s_cbranch_vccnz .LBB0_1495
	s_mul_i32 s4, s2, 7
	s_add_i32 s4, s4, s96
	s_add_i32 s5, s2, 0x700
	s_cmp_eq_u32 s96, 7
	s_cselect_b32 s20, s5, s4
	s_add_i32 s14, s36, 0xffffff80
	s_cmp_ge_i32 s20, s14
	s_cselect_b64 s[4:5], -1, 0
	s_cmpk_gt_i32 s20, 0x1fff
	s_cselect_b64 s[6:7], -1, 0
	s_or_b64 s[4:5], s[4:5], s[6:7]
	s_mov_b64 s[12:13], s[0:1]
	s_and_b64 vcc, exec, s[4:5]
	v_mbcnt_lo_u32_b32 v0, -1, 0
	v_mbcnt_hi_u32_b32 v0, -1, v0
	s_cbranch_vccnz .LBB0_999
	s_waitcnt lgkmcnt(0)
	v_mbcnt_lo_u32_b32 v1, -1, 0
	v_mbcnt_hi_u32_b32 v4, -1, v1
	v_and_b32_e32 v1, 64, v4
	v_add_u32_e32 v5, 64, v1
	v_xor_b32_e32 v1, 1, v4
	v_cmp_lt_i32_e32 vcc, v1, v5
	v_xor_b32_e32 v2, 2, v4
	s_load_dwordx4 s[4:7], s[12:13], 0xa8
	s_load_dwordx4 s[8:11], s[12:13], 0x80
	v_cndmask_b32_e32 v1, v4, v1, vcc
	v_cmp_lt_i32_e32 vcc, v2, v5
	s_waitcnt vmcnt(0)
	v_xor_b32_e32 v8, 16, v4
	s_waitcnt lgkmcnt(0)
	s_add_u32 s16, s4, 0xe200000
	v_cndmask_b32_e32 v2, v4, v2, vcc
	v_lshlrev_b32_e32 v16, 2, v2
	v_xor_b32_e32 v2, 4, v4
	v_cmp_lt_i32_e32 vcc, v2, v5
	v_lshlrev_b32_e32 v6, 1, v0
	v_lshlrev_b32_e32 v14, 3, v0
	v_cndmask_b32_e32 v2, v4, v2, vcc
	v_lshlrev_b32_e32 v17, 2, v2
	v_xor_b32_e32 v2, 8, v4
	v_cmp_lt_i32_e32 vcc, v2, v5
	s_addc_u32 s17, s5, 0
	v_mov_b32_e32 v3, 0
	v_cndmask_b32_e32 v2, v4, v2, vcc
	v_cmp_lt_i32_e32 vcc, v8, v5
	v_lshlrev_b32_e32 v18, 2, v2
	v_lshlrev_b32_e32 v2, 5, v0
	v_cndmask_b32_e32 v8, v4, v8, vcc
	v_lshlrev_b32_e32 v19, 2, v8
	v_xor_b32_e32 v8, 32, v4
	v_and_b32_e32 v2, 0x1e0, v2
	v_ashrrev_i32_e32 v7, 31, v6
	v_cmp_lt_i32_e32 vcc, v8, v5
	s_ashr_i32 s21, s20, 31
	v_ashrrev_i32_e32 v15, 31, v14
	v_lshl_add_u64 v[2:3], s[8:9], 0, v[2:3]
	v_cndmask_b32_e32 v4, v4, v8, vcc
	v_lshlrev_b64 v[8:9], 2, v[6:7]
	s_lshl_b64 s[8:9], s[20:21], 8
	s_lshl_b64 s[18:19], s[20:21], 9
	v_lshlrev_b32_e32 v20, 2, v4
	v_lshl_add_u64 v[4:5], s[10:11], 0, v[8:9]
	v_lshl_add_u64 v[6:7], v[6:7], 1, s[8:9]
	s_mov_b64 s[8:9], 0x3bc00000
	s_ashr_i32 s15, s14, 31
	v_lshl_add_u64 v[8:9], s[18:19], 0, v[8:9]
	v_lshl_add_u64 v[10:11], s[18:19], 0, v[14:15]
	v_lshrrev_b32_e32 v64, 7, v14
	v_and_b32_e32 v65, 0x78, v14
	v_lshl_or_b32 v64, v64, 20, v65
	s_lshl_b32 s100, s20, 7
	v_add_u32_e32 v64, s100, v64
	v_mov_b32_e32 v65, 0
	s_lshl_b32 s101, s14, 7
	s_lshl_b64 s[18:19], s[20:21], 10
	s_lshl_b64 s[22:23], s[20:21], 11
	v_lshlrev_b32_e32 v1, 2, v1
	v_lshl_add_u64 v[6:7], v[6:7], 0, s[8:9]
	s_lshl_b64 s[8:9], s[14:15], 8
	s_lshl_b64 s[10:11], s[14:15], 9
	v_lshl_add_u64 v[12:13], v[14:15], 1, s[18:19]
	s_lshl_b64 s[18:19], s[14:15], 10
	v_lshl_add_u64 v[14:15], v[14:15], 2, s[22:23]
	s_lshl_b64 s[22:23], s[14:15], 11
	s_mov_b64 s[38:39], 0x39600000
	v_mov_b32_e32 v21, 0x358637bd
	s_mov_b32 s3, 0x800000
	s_mov_b32 s15, 0xc200000
	s_mov_b32 s21, 0x3ac00000
	s_mov_b32 s29, 0x4fc00000
	s_mov_b32 s30, 0x3b400000
	s_brev_b32 s31, 10
	s_mov_b32 s34, 0x3a600000
	s_mov_b32 s35, s20
